# XCD barrier: all leaders poll the cross-XCD arrival counter (TOP >= (k+1)*nx) instead of the generation word bumped after the last arriver's atomic round trip; early acquire, run-scan hoist, static pr
# baseline (speedup 1.0000x reference)
; DI unsigned xb_ld(unsigned* p)              { return __hip_atomic_load(p, __ATOMIC_RELAXED, __HIP_MEMORY_SCOPE_AGENT); }
; DI unsigned xb_add(unsigned* p, unsigned v) { return __hip_atomic_fetch_add(p, v, __ATOMIC_RELAXED, __HIP_MEMORY_SCOPE_AGENT); }
; #define XB_SPIN(cond, bar) do { unsigned _sp = 0; while (cond) { __builtin_amdgcn_s_sleep(1); \
;     if ((++_sp & 255u) == 0u) { if (xb_ld(&(bar)[XB_TMO])) break; if (_sp > XB_SPIN_CAP) { atomicAdd(&(bar)[XB_TMO], 1u); break; } } } } while (0)
; DI void xcd_barrier(const XcdBarrier& b) {
;     ...
;         unsigned nloc = b.st[0], nx = b.st[1];
;         if (nloc == 0u) { xcd_barrier_complete(bar, b.x, nloc, nx); b.st[0] = nloc; b.st[1] = nx; }
;         const unsigned old = xb_add(&bar[XB_XSUB(b.x)], 1u);
;         const unsigned gen = old / nloc;
;         if (old + 1u == (gen + 1u) * nloc) {
;             __builtin_amdgcn_fence(__ATOMIC_RELEASE, "agent");
;             asm volatile("s_waitcnt vmcnt(0)" ::: "memory");
;             const unsigned og = xb_add(&bar[XB_TOP], 1u);
;             const unsigned tg = og / nx;
;             if (og + 1u == (tg + 1u) * nx) xb_add(&bar[XB_TOPGEN], 1u);
;             else XB_SPIN(xb_ld(&bar[XB_TOPGEN]) == tg, bar);
;             __builtin_amdgcn_fence(__ATOMIC_ACQUIRE, "agent");
;             xb_add(&bar[XB_XGEN(b.x)], 1u);
;             asm volatile("s_waitcnt vmcnt(0)" ::: "memory");
;         } else {
;             XB_SPIN(xb_ld(&bar[XB_XGEN(b.x)]) == gen, bar);
.LBB0_174:
	s_or_b64 exec, exec, s[4:5]
	v_cvt_f32_u32_e32 v6, v3
	s_waitcnt vmcnt(0)
	v_readfirstlane_b32 s0, v5
	v_sub_u32_e32 v5, 0, v3
	v_rcp_iflag_f32_e32 v6, v6
	v_add_u32_e32 v7, s0, v1
	v_mul_f32_e32 v6, 0x4f7ffffe, v6
	v_cvt_u32_f32_e32 v6, v6
	v_mul_lo_u32 v1, v5, v6
	v_mul_hi_u32 v1, v6, v1
	v_add_u32_e32 v1, v6, v1
	v_mul_hi_u32 v1, v7, v1
	v_mul_lo_u32 v5, v1, v3
	v_sub_u32_e32 v5, v7, v5
	v_add_u32_e32 v6, 1, v1
	v_cmp_ge_u32_e32 vcc, v5, v3
	s_nop 1
	v_cndmask_b32_e32 v1, v1, v6, vcc
	v_sub_u32_e32 v6, v5, v3
	v_cndmask_b32_e32 v5, v5, v6, vcc
	v_add_u32_e32 v6, 1, v1
	v_cmp_ge_u32_e32 vcc, v5, v3
	v_add_u32_e32 v5, 1, v7
	s_nop 0
	v_cndmask_b32_e32 v1, v1, v6, vcc
	v_mul_lo_u32 v6, v3, v1
	v_add_u32_e32 v3, v6, v3
	v_cmp_ne_u32_e32 vcc, v5, v3
	s_and_saveexec_b64 s[0:1], vcc
	s_xor_b64 s[4:5], exec, s[0:1]
	s_cbranch_execz .LBB0_188
	v_readlane_b32 s0, v253, 45
	v_readlane_b32 s1, v253, 46
	s_waitcnt lgkmcnt(0)
	s_nop 3
	buffer_inv sc1
	v_add_u32_e32 v19, 1, v1
	v_mul_lo_u32 v19, v19, v2
	global_load_dword v2, v0, s[0:1] sc1
	s_waitcnt vmcnt(0)
	v_cmp_lt_u32_e32 vcc, v2, v19
	s_and_saveexec_b64 s[6:7], vcc
	s_cbranch_execz .LBB0_187
	s_mov_b32 s0, 1
	s_mov_b64 s[8:9], 0
	s_branch .LBB0_178

; DI unsigned xb_ld(unsigned* p)              { return __hip_atomic_load(p, __ATOMIC_RELAXED, __HIP_MEMORY_SCOPE_AGENT); }
; #define XB_SPIN(cond, bar) do { unsigned _sp = 0; while (cond) { __builtin_amdgcn_s_sleep(1); \
;     if ((++_sp & 255u) == 0u) { if (xb_ld(&(bar)[XB_TMO])) break; if (_sp > XB_SPIN_CAP) { atomicAdd(&(bar)[XB_TMO], 1u); break; } } } } while (0)
; DI void xcd_barrier(const XcdBarrier& b) {
;     ...
;         } else {
;             XB_SPIN(xb_ld(&bar[XB_XGEN(b.x)]) == gen, bar);
.LBB0_180:
	v_readlane_b32 s12, v253, 45
	v_readlane_b32 s13, v253, 46
	s_add_i32 s0, s0, 1
	s_mov_b64 s[14:15], -1
	s_nop 2
	global_load_dword v2, v0, s[12:13] sc1
	s_waitcnt vmcnt(0)
	v_cmp_ge_u32_e32 vcc, v2, v19
	s_orn2_b64 s[12:13], vcc, exec
	s_branch .LBB0_177

; DI unsigned xb_ld(unsigned* p)              { return __hip_atomic_load(p, __ATOMIC_RELAXED, __HIP_MEMORY_SCOPE_AGENT); }
; DI unsigned xb_add(unsigned* p, unsigned v) { return __hip_atomic_fetch_add(p, v, __ATOMIC_RELAXED, __HIP_MEMORY_SCOPE_AGENT); }
; #define XB_SPIN(cond, bar) do { unsigned _sp = 0; while (cond) { __builtin_amdgcn_s_sleep(1); \
;     if ((++_sp & 255u) == 0u) { if (xb_ld(&(bar)[XB_TMO])) break; if (_sp > XB_SPIN_CAP) { atomicAdd(&(bar)[XB_TMO], 1u); break; } } } } while (0)
; DI void xcd_barrier(const XcdBarrier& b) {
;     ...
;             const unsigned og = xb_add(&bar[XB_TOP], 1u);
;             const unsigned tg = og / nx;
;             if (og + 1u == (tg + 1u) * nx) xb_add(&bar[XB_TOPGEN], 1u);
;             else XB_SPIN(xb_ld(&bar[XB_TOPGEN]) == tg, bar);
.LBB0_191:
	s_or_b64 exec, exec, s[8:9]
	v_cvt_f32_u32_e32 v5, v2
	s_waitcnt vmcnt(0)
	v_readfirstlane_b32 s0, v3
	s_mov_b64 s[8:9], -1
	v_rcp_iflag_f32_e32 v5, v5
	v_add_u32_e32 v1, s0, v1
	v_add_u32_e32 v6, 1, v1
	v_readlane_b32 s0, v253, 47
	v_mul_f32_e32 v3, 0x4f7ffffe, v5
	v_cvt_u32_f32_e32 v3, v3
	v_sub_u32_e32 v5, 0, v2
	v_readlane_b32 s1, v253, 48
	v_mul_lo_u32 v5, v5, v3
	v_mul_hi_u32 v5, v3, v5
	v_add_u32_e32 v3, v3, v5
	v_mul_hi_u32 v3, v1, v3
	v_mul_lo_u32 v5, v3, v2
	v_sub_u32_e32 v1, v1, v5
	v_add_u32_e32 v7, 1, v3
	v_cmp_ge_u32_e32 vcc, v1, v2
	v_sub_u32_e32 v5, v1, v2
	s_nop 0
	v_cndmask_b32_e32 v3, v3, v7, vcc
	v_cndmask_b32_e32 v1, v1, v5, vcc
	v_add_u32_e32 v5, 1, v3
	v_cmp_ge_u32_e32 vcc, v1, v2
	s_nop 1
	v_cndmask_b32_e32 v1, v3, v5, vcc
	v_mul_lo_u32 v3, v2, v1
	v_add_u32_e32 v2, v3, v2
	v_mov_b32_e32 v19, v2
	v_cmp_ne_u32_e32 vcc, v6, v2
	v_mov_b64_e32 v[2:3], s[0:1]
	s_and_saveexec_b64 s[6:7], vcc
	s_cbranch_execz .LBB0_203
	v_readlane_b32 s0, v253, 45
	v_readlane_b32 s1, v253, 46
	s_mov_b64 s[10:11], 0
	s_nop 3
	global_load_dword v2, v0, s[0:1] sc1
	s_waitcnt vmcnt(0)
	v_cmp_lt_u32_e32 vcc, v2, v19
	s_and_saveexec_b64 s[8:9], vcc
	s_cbranch_execz .LBB0_202
	s_mov_b32 s0, 1
	s_branch .LBB0_195

; DI unsigned xb_ld(unsigned* p)              { return __hip_atomic_load(p, __ATOMIC_RELAXED, __HIP_MEMORY_SCOPE_AGENT); }
; DI unsigned xb_add(unsigned* p, unsigned v) { return __hip_atomic_fetch_add(p, v, __ATOMIC_RELAXED, __HIP_MEMORY_SCOPE_AGENT); }
; #define XB_SPIN(cond, bar) do { unsigned _sp = 0; while (cond) { __builtin_amdgcn_s_sleep(1); \
;     if ((++_sp & 255u) == 0u) { if (xb_ld(&(bar)[XB_TMO])) break; if (_sp > XB_SPIN_CAP) { atomicAdd(&(bar)[XB_TMO], 1u); break; } } } } while (0)
; DI void xcd_barrier(const XcdBarrier& b) {
;     ...
;             const unsigned og = xb_add(&bar[XB_TOP], 1u);
;             const unsigned tg = og / nx;
;             if (og + 1u == (tg + 1u) * nx) xb_add(&bar[XB_TOPGEN], 1u);
;             else XB_SPIN(xb_ld(&bar[XB_TOPGEN]) == tg, bar);
.LBB0_197:
	v_readlane_b32 s14, v253, 45
	v_readlane_b32 s15, v253, 46
	s_add_i32 s0, s0, 1
	s_mov_b64 s[36:37], -1
	s_nop 2
	global_load_dword v2, v0, s[14:15] sc1
	s_waitcnt vmcnt(0)
	v_cmp_ge_u32_e32 vcc, v2, v19
	s_orn2_b64 s[14:15], vcc, exec
	s_branch .LBB0_194

; DI unsigned xb_ld(unsigned* p)              { return __hip_atomic_load(p, __ATOMIC_RELAXED, __HIP_MEMORY_SCOPE_AGENT); }
; DI unsigned xb_add(unsigned* p, unsigned v) { return __hip_atomic_fetch_add(p, v, __ATOMIC_RELAXED, __HIP_MEMORY_SCOPE_AGENT); }
; #define XB_SPIN(cond, bar) do { unsigned _sp = 0; while (cond) { __builtin_amdgcn_s_sleep(1); \
;     if ((++_sp & 255u) == 0u) { if (xb_ld(&(bar)[XB_TMO])) break; if (_sp > XB_SPIN_CAP) { atomicAdd(&(bar)[XB_TMO], 1u); break; } } } } while (0)
; DI void xcd_barrier(const XcdBarrier& b) {
;     ...
;             const unsigned og = xb_add(&bar[XB_TOP], 1u);
;             const unsigned tg = og / nx;
;             if (og + 1u == (tg + 1u) * nx) xb_add(&bar[XB_TOPGEN], 1u);
;             else XB_SPIN(xb_ld(&bar[XB_TOPGEN]) == tg, bar);
.LBB0_318:
	s_or_b64 exec, exec, s[8:9]
	s_waitcnt vmcnt(0)
	v_readfirstlane_b32 s0, v3
	v_sub_u32_e32 v5, 0, v2
	s_mov_b64 s[8:9], -1
	v_add_u32_e32 v3, s0, v1
	v_cvt_f32_u32_e32 v1, v2
	v_readlane_b32 s0, v253, 47
	v_readlane_b32 s1, v253, 48
	v_rcp_iflag_f32_e32 v1, v1
	s_nop 0
	v_mul_f32_e32 v1, 0x4f7ffffe, v1
	v_cvt_u32_f32_e32 v1, v1
	v_mul_lo_u32 v5, v5, v1
	v_mul_hi_u32 v5, v1, v5
	v_add_u32_e32 v1, v1, v5
	v_mul_hi_u32 v1, v3, v1
	v_mul_lo_u32 v5, v1, v2
	v_sub_u32_e32 v5, v3, v5
	v_cmp_ge_u32_e32 vcc, v5, v2
	v_add_u32_e32 v6, 1, v1
	v_add_u32_e32 v3, 1, v3
	v_cndmask_b32_e32 v1, v1, v6, vcc
	v_sub_u32_e32 v6, v5, v2
	v_cndmask_b32_e32 v5, v5, v6, vcc
	v_cmp_ge_u32_e32 vcc, v5, v2
	v_add_u32_e32 v5, 1, v1
	s_nop 0
	v_cndmask_b32_e32 v1, v1, v5, vcc
	v_mul_lo_u32 v5, v2, v1
	v_add_u32_e32 v2, v5, v2
	v_mov_b32_e32 v19, v2
	v_cmp_ne_u32_e32 vcc, v3, v2
	v_mov_b64_e32 v[2:3], s[0:1]
	s_and_saveexec_b64 s[6:7], vcc
	s_cbranch_execz .LBB0_330
	v_readlane_b32 s0, v253, 45
	v_readlane_b32 s1, v253, 46
	s_mov_b64 s[10:11], 0
	s_nop 3
	global_load_dword v2, v0, s[0:1] sc1
	s_waitcnt vmcnt(0)
	v_cmp_lt_u32_e32 vcc, v2, v19
	s_and_saveexec_b64 s[8:9], vcc
	s_cbranch_execz .LBB0_329
	s_mov_b32 s0, 1
	s_branch .LBB0_322

; DI unsigned xb_ld(unsigned* p)              { return __hip_atomic_load(p, __ATOMIC_RELAXED, __HIP_MEMORY_SCOPE_AGENT); }
; DI unsigned xb_add(unsigned* p, unsigned v) { return __hip_atomic_fetch_add(p, v, __ATOMIC_RELAXED, __HIP_MEMORY_SCOPE_AGENT); }
; #define XB_SPIN(cond, bar) do { unsigned _sp = 0; while (cond) { __builtin_amdgcn_s_sleep(1); \
;     if ((++_sp & 255u) == 0u) { if (xb_ld(&(bar)[XB_TMO])) break; if (_sp > XB_SPIN_CAP) { atomicAdd(&(bar)[XB_TMO], 1u); break; } } } } while (0)
; DI void xcd_barrier(const XcdBarrier& b) {
;     ...
;             const unsigned og = xb_add(&bar[XB_TOP], 1u);
;             const unsigned tg = og / nx;
;             if (og + 1u == (tg + 1u) * nx) xb_add(&bar[XB_TOPGEN], 1u);
;             else XB_SPIN(xb_ld(&bar[XB_TOPGEN]) == tg, bar);
.LBB0_376:
	s_or_b64 exec, exec, s[6:7]
	s_waitcnt vmcnt(0)
	v_readfirstlane_b32 s0, v3
	v_sub_u32_e32 v5, 0, v2
	s_mov_b64 s[6:7], -1
	v_add_u32_e32 v3, s0, v1
	v_cvt_f32_u32_e32 v1, v2
	v_readlane_b32 s0, v253, 47
	v_readlane_b32 s1, v253, 48
	v_rcp_iflag_f32_e32 v1, v1
	s_nop 0
	v_mul_f32_e32 v1, 0x4f7ffffe, v1
	v_cvt_u32_f32_e32 v1, v1
	v_mul_lo_u32 v5, v5, v1
	v_mul_hi_u32 v5, v1, v5
	v_add_u32_e32 v1, v1, v5
	v_mul_hi_u32 v1, v3, v1
	v_mul_lo_u32 v5, v1, v2
	v_sub_u32_e32 v5, v3, v5
	v_cmp_ge_u32_e32 vcc, v5, v2
	v_add_u32_e32 v6, 1, v1
	v_add_u32_e32 v3, 1, v3
	v_cndmask_b32_e32 v1, v1, v6, vcc
	v_sub_u32_e32 v6, v5, v2
	v_cndmask_b32_e32 v5, v5, v6, vcc
	v_cmp_ge_u32_e32 vcc, v5, v2
	v_add_u32_e32 v5, 1, v1
	s_nop 0
	v_cndmask_b32_e32 v1, v1, v5, vcc
	v_mul_lo_u32 v5, v2, v1
	v_add_u32_e32 v2, v5, v2
	v_mov_b32_e32 v19, v2
	v_cmp_ne_u32_e32 vcc, v3, v2
	v_mov_b64_e32 v[2:3], s[0:1]
	s_and_saveexec_b64 s[4:5], vcc
	s_cbranch_execz .LBB0_388
	v_readlane_b32 s0, v253, 45
	v_readlane_b32 s1, v253, 46
	s_mov_b64 s[8:9], 0
	s_nop 3
	global_load_dword v2, v0, s[0:1] sc1
	s_waitcnt vmcnt(0)
	v_cmp_lt_u32_e32 vcc, v2, v19
	s_and_saveexec_b64 s[6:7], vcc
	s_cbranch_execz .LBB0_387
	s_mov_b32 s0, 1
	s_branch .LBB0_380
